# DIFF flash loop: V^T LDS tile re-laid out (pitch 144 B, keys permuted in 16-key groups) so V fragments are read with ds_read_b128 instead of ds_read2_b64
# baseline (speedup 1.0000x reference)
.LBB0_477:
	v_mov_b32_e32 v0, v222
	s_lshl_b64 s[0:1], s[0:1], 1
	v_ashrrev_i32_e32 v2, 1, v0
	v_and_b32_e32 v32, 0xffffffe0, v2
	v_add_u32_e32 v213, s46, v32
	v_and_b32_e32 v215, 31, v0
	v_or_b32_e32 v2, v213, v215
	v_ashrrev_i32_e32 v3, 31, v2
	v_lshl_add_u64 v[2:3], s[60:61], 0, v[2:3]
	v_lshlrev_b64 v[2:3], 10, v[2:3]
	v_lshl_add_u64 v[2:3], s[14:15], 0, v[2:3]
	v_lshrrev_b32_e32 v0, 1, v0
	v_lshl_add_u64 v[2:3], v[2:3], 0, s[0:1]
	v_and_b32_e32 v0, 16, v0
	v_lshl_add_u64 v[2:3], v[2:3], 0, v[0:1]
	v_mov_b32_e32 v33, v222
	global_load_dwordx4 v[130:133], v[2:3], off
	global_load_dwordx4 v[134:137], v[2:3], off offset:32
	global_load_dwordx4 v[138:141], v[2:3], off offset:64
	global_load_dwordx4 v[142:145], v[2:3], off offset:96
	s_xor_b64 s[20:21], s[22:23], -1
	v_ashrrev_i32_e32 v0, 31, v33
	v_lshrrev_b32_e32 v0, 29, v0
	v_add_u32_e32 v0, v33, v0
	v_ashrrev_i32_e32 v2, 3, v0
	v_ashrrev_i32_e32 v3, 31, v2
	v_and_b32_e32 v0, -8, v0
	v_lshlrev_b64 v[4:5], 10, v[2:3]
	v_add_u32_e32 v3, 0x100, v33
	v_sub_u32_e32 v34, v33, v0
	v_ashrrev_i32_e32 v0, 31, v3
	v_lshrrev_b32_e32 v0, 29, v0
	v_add_u32_e32 v0, v3, v0
	v_ashrrev_i32_e32 v10, 3, v0
	v_and_b32_e32 v0, -8, v0
	s_add_u32 s22, s47, s0
	v_lshlrev_b32_e32 v186, 3, v34
	v_sub_u32_e32 v35, v3, v0
	s_addc_u32 s23, s48, s1
	v_ashrrev_i32_e32 v187, 31, v186
	v_ashrrev_i32_e32 v11, 31, v10
	v_lshlrev_b32_e32 v188, 3, v35
	v_lshl_add_u64 v[6:7], s[22:23], 0, v[4:5]
	v_lshlrev_b64 v[8:9], 1, v[186:187]
	v_lshlrev_b64 v[12:13], 10, v[10:11]
	v_ashrrev_i32_e32 v189, 31, v188
	v_lshl_add_u64 v[6:7], v[6:7], 0, v[8:9]
	v_lshl_add_u64 v[14:15], s[22:23], 0, v[12:13]
	v_lshlrev_b64 v[16:17], 1, v[188:189]
	s_waitcnt vmcnt(63) expcnt(7) lgkmcnt(15)
	s_barrier
	v_lshl_add_u64 v[14:15], v[14:15], 0, v[16:17]
	global_load_dwordx4 v[146:149], v[6:7], off
	global_load_dwordx4 v[150:153], v[14:15], off
	v_ashrrev_i32_e32 v6, 3, v33
	v_ashrrev_i32_e32 v7, 31, v6
	v_lshlrev_b32_e32 v0, 3, v33
	v_ashrrev_i32_e32 v20, 3, v3
	v_lshlrev_b64 v[14:15], 14, v[6:7]
	v_and_b32_e32 v0, 56, v0
	v_ashrrev_i32_e32 v21, 31, v20
	v_lshl_add_u64 v[18:19], s[4:5], 0, v[14:15]
	v_lshlrev_b32_e32 v0, 1, v0
	v_lshlrev_b64 v[22:23], 14, v[20:21]
	v_lshl_add_u64 v[18:19], v[18:19], 0, v[0:1]
	v_lshl_add_u64 v[24:25], s[4:5], 0, v[22:23]
	v_add_u32_e32 v3, 0x200, v33
	v_lshl_add_u64 v[24:25], v[24:25], 0, v[0:1]
	global_load_dwordx4 v[154:157], v[18:19], off
	global_load_dwordx4 v[158:161], v[24:25], off
	v_ashrrev_i32_e32 v18, 3, v3
	v_ashrrev_i32_e32 v19, 31, v18
	v_lshlrev_b64 v[24:25], 14, v[18:19]
	v_lshl_add_u64 v[26:27], s[4:5], 0, v[24:25]
	v_lshl_add_u64 v[26:27], v[26:27], 0, v[0:1]
	v_add_u32_e32 v3, 0x300, v33
	global_load_dwordx4 v[162:165], v[26:27], off
	v_ashrrev_i32_e32 v26, 3, v3
	v_ashrrev_i32_e32 v27, 31, v26
	v_lshlrev_b64 v[28:29], 14, v[26:27]
	v_lshl_add_u64 v[30:31], s[4:5], 0, v[28:29]
	v_lshl_add_u64 v[30:31], v[30:31], 0, v[0:1]
	global_load_dwordx4 v[166:169], v[30:31], off
	s_movk_i32 s23, 0x48
	v_mul_lo_u32 v237, v20, s23
	v_lshlrev_b32_e32 v7, 1, v237
	s_movk_i32 s22, 0x48
	v_mul_lo_u32 v236, v6, s23
	v_mul_lo_u32 v239, v2, s22
	v_and_b32_e32 v2, 1, v33
	v_and_b32_e32 v255, 6, v33
	v_lshlrev_b32_e32 v2, 3, v2
	v_lshl_or_b32 v255, v255, 4, v2
	v_add3_u32 v2, v7, v255, s93
	v_lshlrev_b32_e32 v7, 4, v34
	v_lshlrev_b32_e32 v6, 1, v236
	v_mul_lo_u32 v238, v18, s23
	v_mul_lo_u32 v240, v10, s22
	v_lshl_add_u32 v7, v239, 1, v7
	v_lshlrev_b32_e32 v10, 4, v35
	v_add3_u32 v6, v6, v255, s93
	v_lshl_add_u32 v10, v240, 1, v10
	v_mul_lo_u32 v241, v26, s23
	v_bfe_u32 v3, v33, 5, 1
	v_mov_b32_e32 v48, v1
	v_mov_b32_e32 v49, v1
	v_mov_b32_e32 v34, v1
	v_mov_b32_e32 v35, v1
	v_mov_b32_e32 v36, v1
	v_mov_b32_e32 v37, v1
	v_mov_b32_e32 v38, v1
	v_mov_b32_e32 v39, v1
	v_mov_b32_e32 v40, v1
	v_mov_b32_e32 v41, v1
	v_mov_b32_e32 v42, v1
	v_mov_b32_e32 v43, v1
	s_waitcnt vmcnt(5)
	ds_write_b128 v7, v[146:149]
	s_waitcnt vmcnt(4)
	ds_write_b128 v10, v[150:153]
	s_waitcnt vmcnt(3)
	ds_write2_b64 v6, v[154:155], v[156:157] offset1:2
	s_waitcnt vmcnt(2)
	ds_write2_b64 v2, v[158:159], v[160:161] offset1:2
	v_lshlrev_b32_e32 v2, 1, v238
	v_add3_u32 v2, v2, v255, s93
	v_lshlrev_b32_e32 v7, 4, v3
	v_mov_b32_e32 v44, v1
	v_mov_b32_e32 v45, v1
	v_mov_b32_e32 v46, v1
	s_waitcnt vmcnt(1)
	ds_write2_b64 v2, v[162:163], v[164:165] offset1:2
	v_lshlrev_b32_e32 v2, 1, v241
	v_add3_u32 v2, v2, v255, s93
	v_mov_b32_e32 v47, v1
	v_mov_b64_e32 v[64:65], v[48:49]
	v_mov_b64_e32 v[80:81], v[48:49]
	s_waitcnt vmcnt(0)
	ds_write2_b64 v2, v[166:167], v[168:169] offset1:2
	v_and_b32_e32 v2, 31, v33
	v_mul_u32_u24_e32 v6, 0x90, v2
	v_mad_u32_u24 v242, v2, s56, v7
	v_lshlrev_b32_e32 v2, 3, v2
	v_sub_u32_e32 v2, v6, v2
	v_mov_b32_e32 v243, v242
	v_lshlrev_b32_e32 v2, 4, v33
	v_and_b32_e32 v2, 0x70, v2
	v_lshlrev_b32_e32 v6, 2, v3
	v_or_b32_e32 v14, v14, v2
	v_or_b32_e32 v22, v22, v2
	v_or_b32_e32 v24, v24, v2
	v_or_b32_e32 v28, v28, v2
	v_lshl_add_u64 v[2:3], v[12:13], 0, s[0:1]
	v_lshl_add_u64 v[2:3], v[2:3], 0, v[16:17]
	v_lshl_add_u64 v[218:219], s[18:19], 0, v[2:3]
	v_lshl_add_u64 v[2:3], v[4:5], 0, s[0:1]
	v_lshl_add_u64 v[2:3], v[2:3], 0, v[8:9]
	v_mov_b64_e32 v[96:97], v[48:49]
	v_or_b32_e32 v187, 3, v6
	v_or_b32_e32 v190, 2, v6
	v_or_b32_e32 v189, 9, v6
	v_or_b32_e32 v192, 8, v6
	v_or_b32_e32 v191, 11, v6
	v_or_b32_e32 v194, 10, v6
	v_or_b32_e32 v193, 17, v6
	v_or_b32_e32 v196, 16, v6
	v_or_b32_e32 v195, 19, v6
	v_or_b32_e32 v198, 18, v6
	v_or_b32_e32 v197, 25, v6
	v_or_b32_e32 v200, 24, v6
	v_or_b32_e32 v199, 27, v6
	v_or_b32_e32 v202, 26, v6
	v_add_u32_e32 v244, s50, v32
	v_sub_u32_e32 v245, v215, v6
	v_lshl_add_u64 v[204:205], s[16:17], 0, v[14:15]
	v_lshl_add_u64 v[206:207], s[16:17], 0, v[22:23]
	v_lshl_add_u64 v[208:209], s[16:17], 0, v[24:25]
	v_lshl_add_u64 v[216:217], s[16:17], 0, v[28:29]
	v_lshl_add_u64 v[220:221], s[18:19], 0, v[2:3]
	s_mov_b32 s0, 0
	v_mov_b32_e32 v246, 0xff800000
	v_mov_b32_e32 v203, 0
	s_mov_b32 s51, 63
	v_mov_b64_e32 v[62:63], v[46:47]
	v_mov_b64_e32 v[60:61], v[44:45]
	v_mov_b64_e32 v[58:59], v[42:43]
	v_mov_b64_e32 v[56:57], v[40:41]
	v_mov_b64_e32 v[54:55], v[38:39]
	v_mov_b64_e32 v[52:53], v[36:37]
	v_mov_b64_e32 v[50:51], v[34:35]
	v_mov_b64_e32 v[78:79], v[46:47]
	v_mov_b64_e32 v[76:77], v[44:45]
	v_mov_b64_e32 v[74:75], v[42:43]
	v_mov_b64_e32 v[72:73], v[40:41]
	v_mov_b64_e32 v[70:71], v[38:39]
	v_mov_b64_e32 v[68:69], v[36:37]
	v_mov_b64_e32 v[66:67], v[34:35]
	v_mov_b64_e32 v[94:95], v[46:47]
	v_mov_b64_e32 v[92:93], v[44:45]
	v_mov_b64_e32 v[90:91], v[42:43]
	v_mov_b64_e32 v[88:89], v[40:41]
	v_mov_b64_e32 v[86:87], v[38:39]
	v_mov_b64_e32 v[84:85], v[36:37]
	v_mov_b64_e32 v[82:83], v[34:35]
	s_waitcnt lgkmcnt(0)
	s_barrier

.LBB0_483:
	s_xor_b32 s0, s53, 1
	s_mul_i32 s1, s0, 0x2400
	v_lshlrev_b32_e32 v2, 1, v239
	v_lshlrev_b32_e32 v3, 1, v186
	v_add3_u32 v2, s1, v2, v3
	s_waitcnt vmcnt(5)
	ds_write_b128 v2, v[146:149]
	v_lshlrev_b32_e32 v2, 1, v240
	v_lshlrev_b32_e32 v3, 1, v188
	s_mul_i32 s0, s0, 0x2400
	v_add3_u32 v2, s1, v2, v3
	s_add_i32 s1, s1, s0
	s_waitcnt vmcnt(4)
	ds_write_b128 v2, v[150:153]
	v_lshl_add_u32 v2, v236, 1, s1
	v_add3_u32 v2, v2, v255, s93
	s_waitcnt vmcnt(3)
	ds_write2_b64 v2, v[154:155], v[156:157] offset1:2
	v_lshl_add_u32 v2, v237, 1, s1
	v_add3_u32 v2, v2, v255, s93
	s_waitcnt vmcnt(2)
	ds_write2_b64 v2, v[158:159], v[160:161] offset1:2
	v_lshl_add_u32 v2, v238, 1, s1
	v_add3_u32 v2, v2, v255, s93
	s_waitcnt vmcnt(1)
	ds_write2_b64 v2, v[162:163], v[164:165] offset1:2
	v_lshl_add_u32 v2, v241, 1, s1
	v_add3_u32 v2, v2, v255, s93
	s_waitcnt vmcnt(0)
	ds_write2_b64 v2, v[166:167], v[168:169] offset1:2

.LBB0_486:
	s_mul_i32 s0, s53, 0x2400
	v_add_u32_e32 v30, s0, v242
	ds_read_b128 v[2:5], v30
	ds_read_b128 v[6:9], v30 offset:32
	ds_read_b128 v[10:13], v30 offset:4608
	ds_read_b128 v[14:17], v30 offset:4640
	ds_read_b128 v[18:21], v30 offset:64
	ds_read_b128 v[22:25], v30 offset:96
	ds_read_b128 v[26:29], v30 offset:4672
	ds_read_b128 v[30:33], v30 offset:4704
	s_brev_b32 s0, -4
	v_cmp_gt_i32_e32 vcc, s51, v213
	v_cmp_lt_i32_e64 s[0:1], s0, v244
	v_add_u32_e32 v98, 0xffffff81, v213
	s_or_b64 s[0:1], vcc, s[0:1]
	v_cmp_ge_i32_e32 vcc, s51, v98
	s_or_b64 s[26:27], s[0:1], vcc
	s_waitcnt lgkmcnt(5)
	v_mfma_f32_32x32x16_bf16 v[98:113], v[10:13], v[130:133], 0
	s_mul_i32 s0, s53, 0x4800
	v_add_u32_e32 v226, s0, v243
	v_mfma_f32_32x32x16_bf16 v[114:129], v[2:5], v[130:133], 0
	ds_read_b128 v[182:185], v226 offset:18432
	ds_read_b128 v[178:181], v226 offset:18464
	ds_read_b128 v[174:177], v226 offset:18496
	ds_read_b128 v[170:173], v226 offset:18528
	s_waitcnt lgkmcnt(8)
	v_mfma_f32_32x32x16_bf16 v[98:113], v[14:17], v[134:137], v[98:113]
	v_mfma_f32_32x32x16_bf16 v[114:129], v[6:9], v[134:137], v[114:129]
	s_waitcnt lgkmcnt(5)
	v_mfma_f32_32x32x16_bf16 v[98:113], v[26:29], v[138:141], v[98:113]
	v_mfma_f32_32x32x16_bf16 v[114:129], v[18:21], v[138:141], v[114:129]
	s_waitcnt lgkmcnt(4)
	v_mfma_f32_32x32x16_bf16 v[98:113], v[30:33], v[142:145], v[98:113]
	v_mfma_f32_32x32x16_bf16 v[114:129], v[22:25], v[142:145], v[114:129]
	s_and_saveexec_b64 s[0:1], s[26:27]
	s_xor_b64 s[28:29], exec, s[0:1]
	s_cbranch_execz .LBB0_488
	v_add_u32_e32 v15, v245, v244
	v_subrev_u32_e32 v2, 31, v15
	v_cmp_gt_u32_e32 vcc, 2.0, v2
	v_med3_i32 v2, v2, 0, v229
	v_lshlrev_b32_e32 v2, 2, v2
	s_movk_i32 s0, 0xffe1
	ds_read_b32 v2, v2 offset:60000
	v_add3_u32 v14, v215, v244, s0
	v_sub_u32_e32 v11, v14, v187
	v_med3_i32 v3, v11, 0, v229
	v_lshlrev_b32_e32 v3, 2, v3
	ds_read_b32 v3, v3 offset:60000
	s_waitcnt lgkmcnt(1)
	v_fmac_f32_e32 v2, 0x3e38aa3b, v114
	v_cndmask_b32_e32 v114, v230, v2, vcc
	v_subrev_u32_e32 v2, 32, v15
	v_cmp_gt_u32_e32 vcc, 2.0, v2
	v_med3_i32 v2, v2, 0, v229
	v_lshlrev_b32_e32 v2, 2, v2
	ds_read_b32 v2, v2 offset:60000
	v_sub_u32_e32 v16, v14, v190
	v_cmp_gt_u32_e64 s[0:1], 2.0, v11
	v_sub_u32_e32 v13, v14, v189
	v_sub_u32_e32 v12, v14, v192
	s_waitcnt lgkmcnt(0)
	v_fmac_f32_e32 v2, 0x3e38aa3b, v115
	v_cndmask_b32_e32 v115, v230, v2, vcc
	v_med3_i32 v2, v16, 0, v229
	v_lshlrev_b32_e32 v2, 2, v2
	ds_read_b32 v2, v2 offset:60000
	v_cmp_gt_u32_e32 vcc, 2.0, v16
	v_sub_u32_e32 v9, v14, v191
	v_sub_u32_e32 v8, v14, v194
	v_sub_u32_e32 v7, v14, v193
	s_waitcnt lgkmcnt(0)
	v_pk_fma_f32 v[2:3], v[116:117], s[92:93], v[2:3] op_sel_hi:[1,0,1]
	v_sub_u32_e32 v6, v14, v196
	v_cndmask_b32_e64 v117, v230, v3, s[0:1]
	v_cndmask_b32_e32 v116, v230, v2, vcc
	v_med3_i32 v2, v12, 0, v229
	v_med3_i32 v3, v13, 0, v229
	v_lshlrev_b32_e32 v2, 2, v2
	v_lshlrev_b32_e32 v3, 2, v3
	ds_read_b32 v2, v2 offset:60000
	ds_read_b32 v3, v3 offset:60000
	v_cmp_gt_u32_e32 vcc, 2.0, v12
	v_cmp_gt_u32_e64 s[0:1], 2.0, v13
	v_max3_f32 v4, v114, s33, v115
	v_max3_f32 v4, v4, v116, v117
	s_waitcnt lgkmcnt(0)
	v_pk_fma_f32 v[2:3], v[118:119], s[92:93], v[2:3] op_sel_hi:[1,0,1]
	v_sub_u32_e32 v5, v14, v195
	v_cndmask_b32_e64 v119, v230, v3, s[0:1]
	v_cndmask_b32_e32 v118, v230, v2, vcc
	v_med3_i32 v2, v8, 0, v229
	v_med3_i32 v3, v9, 0, v229
	v_lshlrev_b32_e32 v2, 2, v2
	v_lshlrev_b32_e32 v3, 2, v3
	ds_read_b32 v2, v2 offset:60000
	ds_read_b32 v3, v3 offset:60000
	v_cmp_gt_u32_e32 vcc, 2.0, v8
	v_cmp_gt_u32_e64 s[0:1], 2.0, v9
	v_max3_f32 v4, v4, v118, v119
	s_waitcnt lgkmcnt(0)
	v_pk_fma_f32 v[2:3], v[120:121], s[92:93], v[2:3] op_sel_hi:[1,0,1]
	s_nop 0
	v_cndmask_b32_e64 v121, v230, v3, s[0:1]
	v_cndmask_b32_e32 v120, v230, v2, vcc
	v_med3_i32 v2, v6, 0, v229
	v_med3_i32 v3, v7, 0, v229
	v_lshlrev_b32_e32 v2, 2, v2
	v_lshlrev_b32_e32 v3, 2, v3
	ds_read_b32 v2, v2 offset:60000
	ds_read_b32 v3, v3 offset:60000
	v_cmp_gt_u32_e32 vcc, 2.0, v6
	v_cmp_gt_u32_e64 s[0:1], 2.0, v7
	v_max3_f32 v4, v4, v120, v121
	s_waitcnt lgkmcnt(0)
	v_pk_fma_f32 v[2:3], v[122:123], s[92:93], v[2:3] op_sel_hi:[1,0,1]
	s_nop 0
	v_cndmask_b32_e64 v123, v230, v3, s[0:1]
	v_cndmask_b32_e32 v122, v230, v2, vcc
	v_max3_f32 v10, v4, v122, v123
	v_sub_u32_e32 v4, v14, v198
	v_med3_i32 v2, v4, 0, v229
	v_med3_i32 v3, v5, 0, v229
	v_lshlrev_b32_e32 v2, 2, v2
	v_lshlrev_b32_e32 v3, 2, v3
	ds_read_b32 v2, v2 offset:60000
	ds_read_b32 v3, v3 offset:60000
	v_cmp_gt_u32_e32 vcc, 2.0, v4
	v_cmp_gt_u32_e64 s[0:1], 2.0, v5
	s_waitcnt lgkmcnt(0)
	v_pk_fma_f32 v[2:3], v[124:125], s[92:93], v[2:3] op_sel_hi:[1,0,1]
	s_nop 0
	v_cndmask_b32_e32 v124, v230, v2, vcc
	v_sub_u32_e32 v2, v14, v200
	v_med3_i32 v17, v2, 0, v229
	v_cndmask_b32_e64 v125, v230, v3, s[0:1]
	v_sub_u32_e32 v3, v14, v197
	v_lshlrev_b32_e32 v17, 2, v17
	ds_read_b32 v18, v17 offset:60000
	v_med3_i32 v17, v3, 0, v229
	v_lshlrev_b32_e32 v17, 2, v17
	ds_read_b32 v19, v17 offset:60000
	v_cmp_gt_u32_e32 vcc, 2.0, v2
	v_cmp_gt_u32_e64 s[0:1], 2.0, v3
	v_max3_f32 v10, v10, v124, v125
	s_waitcnt lgkmcnt(0)
	v_pk_fma_f32 v[18:19], v[126:127], s[92:93], v[18:19] op_sel_hi:[1,0,1]
	s_nop 0
	v_cndmask_b32_e64 v127, v230, v19, s[0:1]
	v_cndmask_b32_e32 v126, v230, v18, vcc
	v_max3_f32 v17, v10, v126, v127
	v_sub_u32_e32 v10, v14, v202
	v_sub_u32_e32 v14, v14, v199
	v_med3_i32 v18, v10, 0, v229
	v_med3_i32 v19, v14, 0, v229
	v_lshlrev_b32_e32 v18, 2, v18
	v_lshlrev_b32_e32 v19, 2, v19
	ds_read_b32 v18, v18 offset:60000
	ds_read_b32 v19, v19 offset:60000
	v_cmp_gt_u32_e32 vcc, 2.0, v10
	v_cmp_gt_u32_e64 s[0:1], 2.0, v14
	s_waitcnt lgkmcnt(0)
	v_pk_fma_f32 v[18:19], v[128:129], s[92:93], v[18:19] op_sel_hi:[1,0,1]
	s_nop 0
	v_cndmask_b32_e64 v129, v230, v19, s[0:1]
	v_cndmask_b32_e32 v128, v230, v18, vcc
	v_max3_f32 v20, v17, v128, v129
	v_subrev_u32_e32 v17, 63, v15
	v_cmp_gt_u32_e32 vcc, 2.0, v17
	v_med3_i32 v17, v17, 0, v229
	v_lshlrev_b32_e32 v17, 2, v17
	ds_read_b32 v17, v17 offset:60000
	v_subrev_u32_e32 v15, 64, v15
	v_cmp_gt_u32_e64 s[0:1], 2.0, v15
	v_mov_b32_e32 v18, v99
	v_mov_b32_e32 v19, v100
	s_waitcnt lgkmcnt(0)
	v_fmac_f32_e32 v17, 0x3e38aa3b, v98
	v_cndmask_b32_e32 v98, v230, v17, vcc
	v_subrev_u32_e32 v17, 32, v16
	v_med3_i32 v16, v15, 0, v229
	v_med3_i32 v15, v17, 0, v229
	v_lshlrev_b32_e32 v16, 2, v16
	v_lshlrev_b32_e32 v15, 2, v15
	ds_read_b32 v16, v16 offset:60000
	v_cmp_gt_u32_e32 vcc, 2.0, v17
	ds_read_b32 v17, v15 offset:60000
	s_waitcnt lgkmcnt(0)
	v_pk_fma_f32 v[16:17], v[18:19], s[92:93], v[16:17] op_sel_hi:[1,0,1]
	s_nop 0
	v_cndmask_b32_e32 v100, v230, v17, vcc
	v_cndmask_b32_e64 v99, v230, v16, s[0:1]
	v_pk_mov_b32 v[16:17], v[10:11], v[12:13] op_sel:[1,0]
	v_mov_b32_e32 v18, v101
	v_subrev_u32_e32 v11, 32, v17
	v_subrev_u32_e32 v17, 32, v16
	v_med3_i32 v16, v17, 0, v229
	v_cmp_gt_u32_e64 s[0:1], 2.0, v11
	v_med3_i32 v11, v11, 0, v229
	v_lshlrev_b32_e32 v16, 2, v16
	v_lshlrev_b32_e32 v11, 2, v11
	ds_read_b32 v16, v16 offset:60000
	v_cmp_gt_u32_e32 vcc, 2.0, v17
	ds_read_b32 v17, v11 offset:60000
	v_mov_b32_e32 v19, v102
	v_max3_f32 v15, v20, v98, v99
	v_pk_mov_b32 v[12:13], v[12:13], v[8:9] op_sel:[1,0]
	v_pk_mov_b32 v[8:9], v[8:9], v[6:7] op_sel:[1,0]
	s_waitcnt lgkmcnt(0)
	v_pk_fma_f32 v[16:17], v[18:19], s[92:93], v[16:17] op_sel_hi:[1,0,1]
	v_subrev_u32_e32 v13, 32, v13
	v_cndmask_b32_e32 v101, v230, v16, vcc
	v_max3_f32 v11, v15, v100, v101
	v_subrev_u32_e32 v15, 32, v12
	v_cndmask_b32_e64 v102, v230, v17, s[0:1]
	v_med3_i32 v12, v15, 0, v229
	v_cmp_gt_u32_e64 s[0:1], 2.0, v13
	v_med3_i32 v13, v13, 0, v229
	v_lshlrev_b32_e32 v12, 2, v12
	v_lshlrev_b32_e32 v13, 2, v13
	ds_read_b32 v12, v12 offset:60000
	ds_read_b32 v13, v13 offset:60000
	v_mov_b32_e32 v16, v103
	v_mov_b32_e32 v17, v104
	v_cmp_gt_u32_e32 vcc, 2.0, v15
	v_subrev_u32_e32 v9, 32, v9
	s_waitcnt lgkmcnt(0)
	v_pk_fma_f32 v[12:13], v[16:17], s[92:93], v[12:13] op_sel_hi:[1,0,1]
	v_pk_mov_b32 v[6:7], v[6:7], v[4:5] op_sel:[1,0]
	v_cndmask_b32_e32 v103, v230, v12, vcc
	v_subrev_u32_e32 v12, 32, v8
	v_cndmask_b32_e64 v104, v230, v13, s[0:1]
	v_med3_i32 v8, v12, 0, v229
	v_cmp_gt_u32_e64 s[0:1], 2.0, v9
	v_med3_i32 v9, v9, 0, v229
	v_lshlrev_b32_e32 v8, 2, v8
	v_lshlrev_b32_e32 v9, 2, v9
	ds_read_b32 v8, v8 offset:60000
	ds_read_b32 v9, v9 offset:60000
	v_cmp_gt_u32_e32 vcc, 2.0, v12
	v_mov_b32_e32 v12, v105
	v_mov_b32_e32 v13, v106
	v_subrev_u32_e32 v7, 32, v7
	s_waitcnt lgkmcnt(0)
	v_pk_fma_f32 v[8:9], v[12:13], s[92:93], v[8:9] op_sel_hi:[1,0,1]
	v_pk_mov_b32 v[4:5], v[4:5], v[2:3] op_sel:[1,0]
	v_cndmask_b32_e32 v105, v230, v8, vcc
	v_subrev_u32_e32 v8, 32, v6
	v_cndmask_b32_e64 v106, v230, v9, s[0:1]
	v_med3_i32 v6, v8, 0, v229
	v_cmp_gt_u32_e64 s[0:1], 2.0, v7
	v_med3_i32 v7, v7, 0, v229
	v_lshlrev_b32_e32 v6, 2, v6
	v_lshlrev_b32_e32 v7, 2, v7
	ds_read_b32 v6, v6 offset:60000
	ds_read_b32 v7, v7 offset:60000
	v_cmp_gt_u32_e32 vcc, 2.0, v8
	v_mov_b32_e32 v8, v107
	v_mov_b32_e32 v9, v108
	v_subrev_u32_e32 v5, 32, v5
	s_waitcnt lgkmcnt(0)
	v_pk_fma_f32 v[6:7], v[8:9], s[92:93], v[6:7] op_sel_hi:[1,0,1]
	v_max3_f32 v11, v11, v102, v103
	v_cndmask_b32_e32 v107, v230, v6, vcc
	v_subrev_u32_e32 v6, 32, v4
	v_cndmask_b32_e64 v108, v230, v7, s[0:1]
	v_med3_i32 v4, v6, 0, v229
	v_cmp_gt_u32_e64 s[0:1], 2.0, v5
	v_med3_i32 v5, v5, 0, v229
	v_lshlrev_b32_e32 v4, 2, v4
	v_lshlrev_b32_e32 v5, 2, v5
	ds_read_b32 v4, v4 offset:60000
	ds_read_b32 v5, v5 offset:60000
	v_max3_f32 v11, v11, v104, v105
	v_cmp_gt_u32_e32 vcc, 2.0, v6
	v_mov_b32_e32 v6, v109
	v_mov_b32_e32 v7, v110
	s_waitcnt lgkmcnt(0)
	v_pk_fma_f32 v[4:5], v[6:7], s[92:93], v[4:5] op_sel_hi:[1,0,1]
	v_pk_mov_b32 v[2:3], v[2:3], v[10:11] op_sel:[1,0]
	v_cndmask_b32_e32 v109, v230, v4, vcc
	v_subrev_u32_e32 v3, 32, v3
	v_subrev_u32_e32 v4, 32, v2
	v_cndmask_b32_e64 v110, v230, v5, s[0:1]
	v_med3_i32 v2, v4, 0, v229
	v_cmp_gt_u32_e64 s[0:1], 2.0, v3
	v_med3_i32 v3, v3, 0, v229
	v_lshlrev_b32_e32 v2, 2, v2
	v_lshlrev_b32_e32 v3, 2, v3
	ds_read_b32 v2, v2 offset:60000
	ds_read_b32 v3, v3 offset:60000
	v_cmp_gt_u32_e32 vcc, 2.0, v4
	v_mov_b32_e32 v4, v111
	v_mov_b32_e32 v5, v112
	v_max3_f32 v8, v11, v106, v107
	s_waitcnt lgkmcnt(0)
	v_pk_fma_f32 v[2:3], v[4:5], s[92:93], v[2:3] op_sel_hi:[1,0,1]
	v_max3_f32 v6, v8, v108, v109
	v_cndmask_b32_e64 v112, v230, v3, s[0:1]
	v_subrev_u32_e32 v3, 32, v14
	v_cndmask_b32_e32 v111, v230, v2, vcc
	v_cmp_gt_u32_e32 vcc, 2.0, v3
	v_med3_i32 v3, v3, 0, v229
	v_lshlrev_b32_e32 v3, 2, v3
	ds_read_b32 v3, v3 offset:60000
	v_max3_f32 v2, v6, v110, v111
	s_waitcnt lgkmcnt(0)
	v_fmac_f32_e32 v3, 0x3e38aa3b, v113
	v_cndmask_b32_e32 v113, v230, v3, vcc
	v_max3_f32 v2, v2, v112, v113

.LBB0_496:
	s_or_b64 exec, exec, s[0:1]
	v_cvt_pk_bf16_f32 v2, v2, v3
	v_cvt_pk_bf16_f32 v3, v4, v5
	v_cvt_pk_bf16_f32 v4, v6, v7
	v_cvt_pk_bf16_f32 v5, v8, v9
	v_cvt_pk_bf16_f32 v6, v10, v11
	v_cvt_pk_bf16_f32 v7, v12, v13
	v_mfma_f32_32x32x16_bf16 v[82:97], v[182:185], v[2:5], v[82:97]
	v_cvt_pk_bf16_f32 v8, v14, v15
	v_cvt_pk_bf16_f32 v9, v16, v17
	v_cvt_pk_bf16_f32 v10, v18, v19
	v_cvt_pk_bf16_f32 v11, v20, v21
	v_cvt_pk_bf16_f32 v12, v22, v23
	v_cvt_pk_bf16_f32 v13, v24, v25
	v_exp_f32_e32 v33, v33
	v_mfma_f32_32x32x16_bf16 v[82:97], v[178:181], v[6:9], v[82:97]
	v_cvt_pk_bf16_f32 v14, v26, v27
	v_cvt_pk_bf16_f32 v15, v28, v29
	v_cvt_pk_bf16_f32 v16, v30, v31
	v_cvt_pk_bf16_f32 v17, v32, v33
	v_add_f32_e32 v98, v33, v248
	ds_read_b128 v[18:21], v226 offset:23040
	ds_read_b128 v[22:25], v226 offset:23072
	ds_read_b128 v[26:29], v226 offset:23104
	ds_read_b128 v[30:33], v226 offset:23136
	v_mfma_f32_32x32x16_bf16 v[82:97], v[174:177], v[10:13], v[82:97]
	v_add_f32_e32 v203, v203, v98
	v_mfma_f32_32x32x16_bf16 v[82:97], v[170:173], v[14:17], v[82:97]
	s_waitcnt lgkmcnt(3)
	v_mfma_f32_32x32x16_bf16 v[66:81], v[18:21], v[2:5], v[66:81]
	s_waitcnt lgkmcnt(2)
	v_mfma_f32_32x32x16_bf16 v[66:81], v[22:25], v[6:9], v[66:81]
	s_waitcnt lgkmcnt(1)
	v_mfma_f32_32x32x16_bf16 v[66:81], v[26:29], v[10:13], v[66:81]
	s_waitcnt lgkmcnt(0)
	v_mfma_f32_32x32x16_bf16 v[66:81], v[30:33], v[14:17], v[66:81]
	ds_read_b128 v[18:21], v226 offset:27648
	ds_read_b128 v[22:25], v226 offset:27680
	ds_read_b128 v[26:29], v226 offset:27712
	ds_read_b128 v[30:33], v226 offset:27744
	s_waitcnt lgkmcnt(3)
	v_mfma_f32_32x32x16_bf16 v[50:65], v[18:21], v[2:5], v[50:65]
	s_waitcnt lgkmcnt(2)
	v_mfma_f32_32x32x16_bf16 v[50:65], v[22:25], v[6:9], v[50:65]
	s_waitcnt lgkmcnt(1)
	v_mfma_f32_32x32x16_bf16 v[50:65], v[26:29], v[10:13], v[50:65]
	s_waitcnt lgkmcnt(0)
	v_mfma_f32_32x32x16_bf16 v[50:65], v[30:33], v[14:17], v[50:65]
	ds_read_b128 v[18:21], v226 offset:32256
	ds_read_b128 v[22:25], v226 offset:32288
	ds_read_b128 v[26:29], v226 offset:32320
	ds_read_b128 v[30:33], v226 offset:32352
	s_waitcnt lgkmcnt(3)
	v_mfma_f32_32x32x16_bf16 v[34:49], v[18:21], v[2:5], v[34:49]
	s_and_b64 s[0:1], s[22:23], exec
	s_waitcnt lgkmcnt(2)
	v_mfma_f32_32x32x16_bf16 v[34:49], v[22:25], v[6:9], v[34:49]
	s_waitcnt lgkmcnt(1)
	v_mfma_f32_32x32x16_bf16 v[34:49], v[26:29], v[10:13], v[34:49]
	s_waitcnt lgkmcnt(0)
	v_mfma_f32_32x32x16_bf16 v[34:49], v[30:33], v[14:17], v[34:49]
	s_andn2_saveexec_b64 s[24:25], s[24:25]
	s_cbranch_execz .LBB0_482
